# scan L1: conflict-free row mapping for the transposed LDS reads of the four tr x tr products (rows 8g+{0,2,4,6} / {1,3,5,7} on both operands); on top of the PW MM load batching
# baseline (speedup 1.0000x reference)
.LBB0_866:
	s_waitcnt lgkmcnt(0)
	s_barrier
	v_add_u32_e32 v18, v70, v71
	v_bfe_u32 v172, v0, 2, 2
	v_mul_u32_u24_e32 v172, 0x90, v172
	v_add_u32_e32 v173, v18, v172
	v_add_u32_e32 v174, v83, v172
	v_add_u32_e32 v175, v84, v172
	ds_read_b64_tr_b16 v[10:11], v173
	ds_read_b64_tr_b16 v[12:13], v173 offset:144
	ds_read_b64_tr_b16 v[14:15], v174 offset:18432
	ds_read_b64_tr_b16 v[16:17], v174 offset:18576
	ds_read_b64_tr_b16 v[122:123], v173 offset:4608
	ds_read_b64_tr_b16 v[124:125], v173 offset:4752
	ds_read_b64_tr_b16 v[22:23], v174 offset:23184
	ds_read_b64_tr_b16 v[20:21], v174 offset:23040
	ds_read_b64_tr_b16 v[130:131], v174 offset:27648
	ds_read_b64_tr_b16 v[132:133], v174 offset:27792
	ds_read_b64_tr_b16 v[136:137], v174 offset:32400
	ds_read_b64_tr_b16 v[134:135], v174 offset:32256
	ds_read_b64_tr_b16 v[142:143], v173 offset:9216
	ds_read_b64_tr_b16 v[144:145], v173 offset:9360
	ds_read_b64_tr_b16 v[146:147], v173 offset:13824
	ds_read_b64_tr_b16 v[148:149], v173 offset:13968
	s_waitcnt lgkmcnt(12)
	v_mfma_f32_16x16x32_bf16 v[126:129], v[10:13], v[14:17], 0
	ds_read_b64_tr_b16 v[152:153], v175 offset:23184
	ds_read_b64_tr_b16 v[154:155], v175 offset:27648
	ds_read_b64_tr_b16 v[156:157], v175 offset:27792
	ds_read_b64_tr_b16 v[158:159], v175 offset:32256
	v_mov_b32_e32 v24, s29
	v_mov_b32_e32 v64, s29
	s_waitcnt lgkmcnt(6)
	v_mfma_f32_16x16x32_bf16 v[14:17], v[142:145], v[14:17], 0
	v_readlane_b32 s12, v250, 5
	v_readlane_b32 s26, v250, 19
	v_readlane_b32 s27, v250, 20
	v_mfma_f32_16x16x32_bf16 v[126:129], v[122:125], v[20:23], v[126:129]
	s_andn2_b64 vcc, exec, s[10:11]
	v_readlane_b32 s13, v250, 6
	v_readlane_b32 s14, v250, 7
	v_mfma_f32_16x16x32_bf16 v[138:141], v[10:13], v[130:133], 0
	v_readlane_b32 s15, v250, 8
	s_nop 2
	v_cndmask_b32_e64 v25, v24, v126, s[58:59]
	v_cndmask_b32_e64 v65, v127, 0, s[60:61]
	s_waitcnt lgkmcnt(4)
	v_mfma_f32_16x16x32_bf16 v[14:17], v[146:149], v[20:23], v[14:17]
	v_readlane_b32 s16, v250, 9
	v_readlane_b32 s17, v250, 10
	v_readlane_b32 s18, v250, 11
	v_mfma_f32_16x16x32_bf16 v[20:23], v[142:145], v[130:133], 0
	ds_read_b64_tr_b16 v[130:131], v175 offset:18432
	ds_read_b64_tr_b16 v[132:133], v175 offset:18576
	ds_read_b64_tr_b16 v[150:151], v175 offset:23040
	ds_read_b64_tr_b16 v[160:161], v175 offset:32400
	v_cndmask_b32_e64 v24, v14, v24, s[60:61]
	v_cndmask_b32_e64 v126, v15, 0, s[62:63]
	v_mfma_f32_16x16x32_bf16 v[138:141], v[122:125], v[134:137], v[138:141]
	v_cvt_pk_bf16_f32 v14, v25, v65
	v_readlane_b32 s19, v250, 12
	v_readlane_b32 s20, v250, 13
	v_mfma_f32_16x16x32_bf16 v[20:23], v[146:149], v[134:137], v[20:23]
	v_cndmask_b32_e64 v134, 0, v128, s[64:65]
	s_nop 2
	v_cndmask_b32_e64 v19, v64, v138, s[58:59]
	v_cndmask_b32_e64 v135, 0, v141, s[68:69]
	v_cndmask_b32_e64 v136, 0, v129, s[68:69]
	v_cndmask_b32_e64 v128, v16, 0, s[66:67]
	v_cndmask_b32_e64 v64, v20, v64, s[60:61]
	v_cndmask_b32_e64 v20, v139, 0, s[60:61]
	v_cndmask_b32_e64 v121, v21, 0, s[62:63]
	v_cndmask_b32_e64 v21, 0, v140, s[64:65]
	v_cndmask_b32_e64 v127, v22, 0, s[66:67]
	v_cndmask_b32_e64 v129, v17, 0, s[70:71]
	v_cvt_pk_bf16_f32 v15, v134, v136
	v_add_u32_e32 v22, v72, v79
	v_cvt_pk_bf16_f32 v20, v19, v20
	v_cvt_pk_bf16_f32 v21, v21, v135
	v_cndmask_b32_e64 v23, v23, 0, s[70:71]
	ds_write_b64 v22, v[14:15]
	s_waitcnt lgkmcnt(3)
	v_mfma_f32_16x16x32_bf16 v[14:17], v[10:13], v[130:133], 0
	ds_write_b64 v85, v[20:21]
	v_cvt_pk_bf16_f32 v20, v24, v126
	v_cvt_pk_bf16_f32 v21, v128, v129
	v_mfma_f32_16x16x32_bf16 v[10:13], v[10:13], v[154:157], 0
	ds_write_b64 v86, v[20:21]
	v_cvt_pk_bf16_f32 v21, v127, v23
	v_cvt_pk_bf16_f32 v20, v64, v121
	v_mfma_f32_16x16x32_bf16 v[126:129], v[142:145], v[130:133], 0
	ds_write_b64 v87, v[20:21]
	v_add_u32_e32 v64, v73, v79
	v_mov_b32_e32 v24, s29
	v_mfma_f32_16x16x32_bf16 v[130:133], v[142:145], v[154:157], 0
	v_readlane_b32 s21, v250, 14
	v_readlane_b32 s22, v250, 15
	v_readlane_b32 s23, v250, 16
	s_waitcnt lgkmcnt(5)
	v_mfma_f32_16x16x32_bf16 v[14:17], v[122:125], v[150:153], v[14:17]
	v_readlane_b32 s24, v250, 17
	v_readlane_b32 s25, v250, 18
	s_waitcnt lgkmcnt(4)
	v_mfma_f32_16x16x32_bf16 v[122:125], v[122:125], v[158:161], v[10:13]
	s_nop 2
	v_add_f32_e32 v10, 1.0, v25
	v_add_f32_e32 v11, 1.0, v65
	v_add_f32_e32 v12, 1.0, v134
	v_add_f32_e32 v13, 1.0, v136
	v_cndmask_b32_e64 v10, v25, v10, s[72:73]
	v_cndmask_b32_e64 v11, v65, v11, s[74:75]
	v_cndmask_b32_e64 v12, v134, v12, s[76:77]
	v_mfma_f32_16x16x32_bf16 v[126:129], v[146:149], v[150:153], v[126:129]
	v_cndmask_b32_e64 v13, v136, v13, s[78:79]
	v_cvt_pk_bf16_f32 v20, v10, v11
	v_cvt_pk_bf16_f32 v21, v12, v13
	ds_write_b64 v64, v[20:21]
	v_mfma_f32_16x16x32_bf16 v[130:133], v[146:149], v[158:161], v[130:133]
	v_mov_b32_e32 v20, s29
	v_cndmask_b32_e64 v21, v20, v14, s[80:81]
	v_mov_b32_e32 v14, s29
	v_cndmask_b32_e64 v25, v15, 0, s[82:83]
	v_cndmask_b32_e64 v16, 0, v16, s[86:87]
	v_cndmask_b32_e64 v17, 0, v17, s[90:91]
	v_cndmask_b32_e64 v19, v24, v122, s[80:81]
	v_cndmask_b32_e64 v23, v126, v14, s[82:83]
	v_cndmask_b32_e64 v24, v123, 0, s[82:83]
	v_cndmask_b32_e64 v122, 0, v124, s[86:87]
	v_cndmask_b32_e64 v125, 0, v125, s[90:91]
	v_cvt_pk_bf16_f32 v14, v21, v25
	v_cvt_pk_bf16_f32 v15, v16, v17
	v_cndmask_b32_e64 v121, v127, 0, s[84:85]
	v_cndmask_b32_e64 v124, v128, 0, s[88:89]
	v_cndmask_b32_e64 v127, v129, 0, s[92:93]
	ds_write_b64 v22, v[14:15] offset:2304
	v_cvt_pk_bf16_f32 v14, v19, v24
	v_cvt_pk_bf16_f32 v15, v122, v125
	v_cndmask_b32_e64 v20, v130, v20, s[82:83]
	v_cndmask_b32_e64 v65, v131, 0, s[84:85]
	v_cndmask_b32_e64 v123, v132, 0, s[88:89]
	v_cndmask_b32_e64 v126, v133, 0, s[92:93]
	ds_write_b64 v85, v[14:15] offset:2304
	v_cvt_pk_bf16_f32 v14, v23, v121
	v_cvt_pk_bf16_f32 v15, v124, v127
	ds_write_b64 v86, v[14:15] offset:2304
	v_cvt_pk_bf16_f32 v14, v20, v65
	v_cvt_pk_bf16_f32 v15, v123, v126
	v_add_f32_e32 v19, 1.0, v16
	ds_write_b64 v87, v[14:15] offset:2304
	v_add_f32_e32 v14, 1.0, v21
	v_add_f32_e32 v15, 1.0, v25
	v_cndmask_b32_e64 v16, v16, v19, s[0:1]
	v_add_f32_e32 v19, 1.0, v17
	v_cndmask_b32_e64 v14, v21, v14, s[94:95]
	v_cndmask_b32_e64 v15, v25, v15, s[96:97]
	v_cndmask_b32_e64 v17, v17, v19, s[2:3]
	v_cvt_pk_bf16_f32 v20, v14, v15
	v_cvt_pk_bf16_f32 v21, v16, v17
	ds_write_b64 v64, v[20:21] offset:2304
	s_waitcnt lgkmcnt(0)
	s_barrier
	ds_read_b64_tr_b16 v[122:123], v88
	ds_read_b64_tr_b16 v[124:125], v88 offset:576
	v_add_u32_e32 v24, v74, v79
	ds_read_b128 v[126:129], v24
	ds_read_b64_tr_b16 v[130:131], v89 offset:4608
	ds_read_b64_tr_b16 v[132:133], v89 offset:5184
	ds_read_b128 v[134:137], v24 offset:64
	v_add_u32_e32 v25, v75, v79
	s_waitcnt lgkmcnt(3)
	v_mfma_f32_16x16x32_bf16 v[126:129], v[122:125], v[126:129], 0
	ds_read_b64_tr_b16 v[138:139], v18
	ds_read_b64_tr_b16 v[140:141], v18 offset:576
	ds_read_b128 v[142:145], v25 offset:64512
	v_add_u32_e32 v21, v74, v66
	s_waitcnt lgkmcnt(3)
	v_mfma_f32_16x16x32_bf16 v[126:129], v[130:133], v[134:137], v[126:129]
	ds_read_b64_tr_b16 v[134:135], v18 offset:4608
	ds_read_b64_tr_b16 v[136:137], v18 offset:5184
	ds_read_b128 v[146:149], v25 offset:64576
	ds_read_b64_tr_b16 v[150:151], v90
	ds_read_b64_tr_b16 v[152:153], v90 offset:576
	ds_read_b64_tr_b16 v[154:155], v91 offset:4608
	ds_read_b128 v[158:161], v25 offset:55296
	ds_read_b64_tr_b16 v[156:157], v91 offset:5184
	s_waitcnt lgkmcnt(8)
	v_mfma_f32_16x16x32_bf16 v[142:145], v[138:141], v[142:145], 0
	v_add_u32_e32 v23, v75, v66
	v_add_u32_e32 v20, v76, v79
	v_add_u32_e32 v19, v76, v66
	s_waitcnt lgkmcnt(5)
	v_mfma_f32_16x16x32_bf16 v[142:145], v[134:137], v[146:149], v[142:145]
	ds_read_b128 v[146:149], v25 offset:55360
	v_add_u32_e32 v121, v77, v79
	s_waitcnt lgkmcnt(2)
	v_mfma_f32_16x16x32_bf16 v[142:145], v[150:153], v[158:161], v[142:145]
	ds_read_b128 v[158:161], v23 offset:64512
	s_waitcnt lgkmcnt(1)
	v_mfma_f32_16x16x32_bf16 v[142:145], v[154:157], v[146:149], v[142:145]
	ds_read_b128 v[146:149], v21
	s_waitcnt lgkmcnt(0)
	v_mfma_f32_16x16x32_bf16 v[122:125], v[122:125], v[146:149], 0
	ds_read_b128 v[146:149], v21 offset:64
	v_mfma_f32_16x16x32_bf16 v[138:141], v[138:141], v[158:161], 0
	v_cvt_pk_bf16_f32 v158, v126, v127
	v_cvt_pk_bf16_f32 v159, v128, v129
	s_waitcnt lgkmcnt(0)
	v_mfma_f32_16x16x32_bf16 v[122:125], v[130:133], v[146:149], v[122:125]
	ds_read_b128 v[130:133], v23 offset:64576
	ds_read_b128 v[146:149], v23 offset:55296
	ds_read_b128 v[168:171], v23 offset:55360
	s_waitcnt lgkmcnt(2)
	v_mfma_f32_16x16x32_bf16 v[126:129], v[134:137], v[130:133], v[138:141]
	v_cvt_pk_bf16_f32 v130, v142, v143
	v_cvt_pk_bf16_f32 v131, v144, v145
	ds_write2st64_b64 v20, v[158:159], v[130:131] offset0:36 offset1:54
	s_waitcnt lgkmcnt(2)
	v_mfma_f32_16x16x32_bf16 v[126:129], v[150:153], v[146:149], v[126:129]
	v_cvt_pk_bf16_f32 v130, v122, v123
	v_cvt_pk_bf16_f32 v131, v124, v125
	v_add_u32_e32 v150, v72, v66
	s_waitcnt lgkmcnt(1)
	v_mfma_f32_16x16x32_bf16 v[122:125], v[154:157], v[168:171], v[126:129]
	v_add_u32_e32 v151, v77, v66
	v_add_u32_e32 v152, v73, v66
	s_nop 5
	v_cvt_pk_bf16_f32 v122, v122, v123
	v_cvt_pk_bf16_f32 v123, v124, v125
	ds_write2st64_b64 v19, v[130:131], v[122:123] offset0:36 offset1:54
	s_waitcnt lgkmcnt(0)
	s_barrier
	ds_read_b64_tr_b16 v[122:123], v18 offset:18432
	ds_read_b64_tr_b16 v[124:125], v18 offset:19008
	ds_read_b128 v[126:129], v25 offset:18432
	ds_read_b64_tr_b16 v[130:131], v18 offset:23040
	ds_read_b64_tr_b16 v[132:133], v18 offset:23616
	ds_read_b128 v[138:141], v25 offset:18496
	ds_read_b64_tr_b16 v[142:143], v92
	ds_read_b64_tr_b16 v[144:145], v92 offset:576
	ds_read_b64_tr_b16 v[146:147], v93 offset:4608
	s_waitcnt lgkmcnt(6)
	v_mfma_f32_16x16x32_bf16 v[134:137], v[122:125], v[126:129], 0
	s_waitcnt lgkmcnt(1)
	v_mfma_f32_16x16x32_bf16 v[10:13], v[142:145], v[126:129], v[10:13]
	ds_read_b64_tr_b16 v[148:149], v93 offset:5184
	ds_read_b128 v[126:129], v23 offset:18432
	v_mfma_f32_16x16x32_bf16 v[134:137], v[130:133], v[138:141], v[134:137]
	s_waitcnt lgkmcnt(1)
	v_mfma_f32_16x16x32_bf16 v[10:13], v[146:149], v[138:141], v[10:13]
	ds_read_b128 v[138:141], v23 offset:18496
	s_nop 4
	v_cvt_pk_bf16_f32 v134, v134, v135
	v_cvt_pk_bf16_f32 v135, v136, v137
	s_waitcnt lgkmcnt(1)
	v_mfma_f32_16x16x32_bf16 v[122:125], v[122:125], v[126:129], 0
	ds_write_b64 v22, v[134:135]
	v_cvt_pk_bf16_f32 v134, v10, v11
	v_cvt_pk_bf16_f32 v135, v12, v13
	v_mfma_f32_16x16x32_bf16 v[14:17], v[142:145], v[126:129], v[14:17]
	ds_write_b64 v121, v[134:135]
	s_waitcnt lgkmcnt(2)
	v_mfma_f32_16x16x32_bf16 v[122:125], v[130:133], v[138:141], v[122:125]
	v_mfma_f32_16x16x32_bf16 v[14:17], v[146:149], v[138:141], v[14:17]
	s_nop 6
	v_cvt_pk_bf16_f32 v122, v122, v123
	v_cvt_pk_bf16_f32 v123, v124, v125
	ds_write_b64 v150, v[122:123]
	v_cvt_pk_bf16_f32 v122, v14, v15
	v_cvt_pk_bf16_f32 v123, v16, v17
	ds_write_b64 v151, v[122:123]
	s_waitcnt lgkmcnt(0)
	s_barrier
	ds_read_b64_tr_b16 v[122:123], v88
	ds_read_b64_tr_b16 v[124:125], v88 offset:576
	ds_read_b128 v[126:129], v24
	ds_read_b64_tr_b16 v[130:131], v89 offset:4608
	ds_read_b64_tr_b16 v[132:133], v89 offset:5184
	ds_read_b128 v[138:141], v24 offset:64
	ds_read_b64_tr_b16 v[142:143], v94
	ds_read_b64_tr_b16 v[144:145], v94 offset:576
	ds_read_b64_tr_b16 v[146:147], v95 offset:4608
	ds_read_b64_tr_b16 v[148:149], v95 offset:5184
	s_waitcnt lgkmcnt(7)
	v_mfma_f32_16x16x32_bf16 v[134:137], v[122:125], v[126:129], 0
	s_waitcnt lgkmcnt(2)
	v_mfma_f32_16x16x32_bf16 v[10:13], v[142:145], v[126:129], v[10:13]
	v_mfma_f32_16x16x32_bf16 v[134:137], v[130:133], v[138:141], v[134:137]
	s_waitcnt lgkmcnt(0)
	v_mfma_f32_16x16x32_bf16 v[10:13], v[146:149], v[138:141], v[10:13]
	ds_read_b128 v[126:129], v21
	ds_read_b128 v[138:141], v21 offset:64
	s_nop 3
	v_cvt_pk_bf16_f32 v134, v134, v135
	v_cvt_pk_bf16_f32 v135, v136, v137
	s_waitcnt lgkmcnt(1)
	v_mfma_f32_16x16x32_bf16 v[122:125], v[122:125], v[126:129], 0
	ds_write_b64 v20, v[134:135] offset:18432
	v_mfma_f32_16x16x32_bf16 v[14:17], v[142:145], v[126:129], v[14:17]
	s_waitcnt lgkmcnt(1)
	v_mfma_f32_16x16x32_bf16 v[122:125], v[130:133], v[138:141], v[122:125]
	v_cvt_pk_bf16_f32 v130, v10, v11
	v_cvt_pk_bf16_f32 v131, v12, v13
	ds_write_b64 v64, v[130:131]
	v_mfma_f32_16x16x32_bf16 v[14:17], v[146:149], v[138:141], v[14:17]
	s_nop 3
	v_cvt_pk_bf16_f32 v122, v122, v123
	v_cvt_pk_bf16_f32 v123, v124, v125
	ds_write_b64 v19, v[122:123] offset:18432
	s_nop 0
	v_cvt_pk_bf16_f32 v122, v14, v15
	v_cvt_pk_bf16_f32 v123, v16, v17
	ds_write_b64 v152, v[122:123]
	s_waitcnt lgkmcnt(0)
	s_barrier
	ds_read_b64_tr_b16 v[122:123], v18 offset:18432
	ds_read_b64_tr_b16 v[124:125], v18 offset:19008
	ds_read_b128 v[126:129], v25 offset:18432
	ds_read_b64_tr_b16 v[130:131], v18 offset:23040
	ds_read_b64_tr_b16 v[132:133], v18 offset:23616
	ds_read_b128 v[138:141], v25 offset:18496
	ds_read_b64_tr_b16 v[142:143], v92
	ds_read_b64_tr_b16 v[144:145], v92 offset:576
	ds_read_b64_tr_b16 v[146:147], v93 offset:4608
	ds_read_b64_tr_b16 v[148:149], v93 offset:5184
	s_waitcnt lgkmcnt(7)
	v_mfma_f32_16x16x32_bf16 v[134:137], v[122:125], v[126:129], 0
	s_waitcnt lgkmcnt(2)
	v_mfma_f32_16x16x32_bf16 v[10:13], v[142:145], v[126:129], v[10:13]
	v_mfma_f32_16x16x32_bf16 v[134:137], v[130:133], v[138:141], v[134:137]
	s_waitcnt lgkmcnt(0)
	v_mfma_f32_16x16x32_bf16 v[10:13], v[146:149], v[138:141], v[10:13]
	ds_read_b128 v[126:129], v23 offset:18432
	ds_read_b128 v[138:141], v23 offset:18496
	s_nop 3
	v_cvt_pk_bf16_f32 v134, v134, v135
	v_cvt_pk_bf16_f32 v135, v136, v137
	s_waitcnt lgkmcnt(1)
	v_mfma_f32_16x16x32_bf16 v[122:125], v[122:125], v[126:129], 0
	ds_write_b64 v22, v[134:135]
	v_mfma_f32_16x16x32_bf16 v[14:17], v[142:145], v[126:129], v[14:17]
	s_waitcnt lgkmcnt(1)
	v_mfma_f32_16x16x32_bf16 v[122:125], v[130:133], v[138:141], v[122:125]
	v_cvt_pk_bf16_f32 v130, v10, v11
	v_cvt_pk_bf16_f32 v131, v12, v13
	ds_write_b64 v121, v[130:131]
	v_mfma_f32_16x16x32_bf16 v[14:17], v[146:149], v[138:141], v[14:17]
	s_nop 3
	v_cvt_pk_bf16_f32 v122, v122, v123
	v_cvt_pk_bf16_f32 v123, v124, v125
	ds_write_b64 v150, v[122:123]
	s_nop 0
	v_cvt_pk_bf16_f32 v122, v14, v15
	v_cvt_pk_bf16_f32 v123, v16, v17
	ds_write_b64 v151, v[122:123]
	s_waitcnt lgkmcnt(0)
	s_barrier
	ds_read_b64_tr_b16 v[122:123], v88
	ds_read_b64_tr_b16 v[124:125], v88 offset:576
	ds_read_b128 v[126:129], v24
	ds_read_b64_tr_b16 v[130:131], v89 offset:4608
	ds_read_b64_tr_b16 v[132:133], v89 offset:5184
	ds_read_b128 v[138:141], v24 offset:64
	ds_read_b64_tr_b16 v[142:143], v94
	ds_read_b64_tr_b16 v[144:145], v94 offset:576
	ds_read_b64_tr_b16 v[146:147], v95 offset:4608
	ds_read_b64_tr_b16 v[148:149], v95 offset:5184
	s_waitcnt lgkmcnt(7)
	v_mfma_f32_16x16x32_bf16 v[134:137], v[122:125], v[126:129], 0
	s_waitcnt lgkmcnt(2)
	v_mfma_f32_16x16x32_bf16 v[10:13], v[142:145], v[126:129], v[10:13]
	v_mfma_f32_16x16x32_bf16 v[134:137], v[130:133], v[138:141], v[134:137]
	s_waitcnt lgkmcnt(0)
	v_mfma_f32_16x16x32_bf16 v[10:13], v[146:149], v[138:141], v[10:13]
	ds_read_b128 v[126:129], v21
	ds_read_b128 v[138:141], v21 offset:64
	s_nop 3
	v_cvt_pk_bf16_f32 v134, v134, v135
	v_cvt_pk_bf16_f32 v135, v136, v137
	s_waitcnt lgkmcnt(1)
	v_mfma_f32_16x16x32_bf16 v[122:125], v[122:125], v[126:129], 0
	ds_write_b64 v20, v[134:135] offset:18432
	v_mfma_f32_16x16x32_bf16 v[14:17], v[142:145], v[126:129], v[14:17]
	s_waitcnt lgkmcnt(1)
	v_mfma_f32_16x16x32_bf16 v[122:125], v[130:133], v[138:141], v[122:125]
	v_cvt_pk_bf16_f32 v130, v10, v11
	v_cvt_pk_bf16_f32 v131, v12, v13
	ds_write_b64 v64, v[130:131]
	v_mfma_f32_16x16x32_bf16 v[14:17], v[146:149], v[138:141], v[14:17]
	s_nop 3
	v_cvt_pk_bf16_f32 v64, v122, v123
	v_cvt_pk_bf16_f32 v65, v124, v125
	ds_write_b64 v19, v[64:65] offset:18432
	s_nop 0
	v_cvt_pk_bf16_f32 v64, v14, v15
	v_cvt_pk_bf16_f32 v65, v16, v17
	ds_write_b64 v152, v[64:65]
	s_waitcnt lgkmcnt(0)
	s_barrier
	ds_read_b64_tr_b16 v[122:123], v92
	ds_read_b64_tr_b16 v[124:125], v92 offset:576
	ds_read_b128 v[126:129], v25 offset:18432
	ds_read_b64_tr_b16 v[130:131], v93 offset:4608
	ds_read_b64_tr_b16 v[132:133], v93 offset:5184
	s_waitcnt lgkmcnt(2)
	v_mfma_f32_16x16x32_bf16 v[10:13], v[122:125], v[126:129], v[10:13]
	ds_read_b128 v[126:129], v25 offset:18496
	v_lshl_add_u64 v[64:65], s[26:27], 0, v[60:61]
	s_waitcnt lgkmcnt(0)
	v_mfma_f32_16x16x32_bf16 v[10:13], v[130:133], v[126:129], v[10:13]
	ds_read_b128 v[126:129], v23 offset:18432
	ds_read_b128 v[134:137], v23 offset:18496
	s_waitcnt lgkmcnt(1)
	v_mfma_f32_16x16x32_bf16 v[14:17], v[122:125], v[126:129], v[14:17]
	s_nop 3
	v_cvt_pk_bf16_f32 v10, v10, v11
	v_cvt_pk_bf16_f32 v11, v12, v13
	ds_write_b64 v121, v[10:11]
	s_waitcnt lgkmcnt(1)
	v_mfma_f32_16x16x32_bf16 v[10:13], v[130:133], v[134:137], v[14:17]
	s_nop 7
	v_cvt_pk_bf16_f32 v10, v10, v11
	v_cvt_pk_bf16_f32 v11, v12, v13
	ds_write_b64 v151, v[10:11]
	s_waitcnt lgkmcnt(0)
	s_barrier
	ds_read_b64_tr_b16 v[10:11], v94
	ds_read_b64_tr_b16 v[12:13], v94 offset:576
	ds_read_b128 v[14:17], v25 offset:27648
	ds_read_b64_tr_b16 v[122:123], v95 offset:4608
	ds_read_b64_tr_b16 v[124:125], v95 offset:5184
	ds_read_b128 v[126:129], v25 offset:27712
	s_waitcnt lgkmcnt(3)
	v_mfma_f32_16x16x32_bf16 v[14:17], v[10:13], v[14:17], 0
	s_waitcnt lgkmcnt(0)
	v_mfma_f32_16x16x32_bf16 v[14:17], v[122:125], v[126:129], v[14:17]
	ds_read_b128 v[126:129], v23 offset:27648
	ds_read_b128 v[130:133], v23 offset:27712
	s_waitcnt lgkmcnt(1)
	v_mfma_f32_16x16x32_bf16 v[10:13], v[10:13], v[126:129], 0
	s_nop 3
	v_cvt_pk_bf16_f32 v14, v14, v15
	v_cvt_pk_bf16_f32 v15, v16, v17
	ds_write_b64 v22, v[14:15]
	s_waitcnt lgkmcnt(1)
	v_mfma_f32_16x16x32_bf16 v[10:13], v[122:125], v[130:133], v[10:13]
	s_nop 7
	v_cvt_pk_bf16_f32 v10, v10, v11
	v_cvt_pk_bf16_f32 v11, v12, v13
	ds_write_b64 v150, v[10:11]
	s_waitcnt lgkmcnt(0)
	s_barrier
	ds_read_b64_tr_b16 v[10:11], v18 offset:9216
	ds_read_b64_tr_b16 v[12:13], v18 offset:9792
	ds_read_b128 v[14:17], v25 offset:64512
	ds_read_b64_tr_b16 v[122:123], v18 offset:13824
	ds_read_b64_tr_b16 v[124:125], v18 offset:14400
	ds_read_b128 v[126:129], v25 offset:64576
	s_waitcnt lgkmcnt(3)
	v_mfma_f32_16x16x32_bf16 v[14:17], v[10:13], v[14:17], 0
	ds_read_b64_tr_b16 v[130:131], v96
	ds_read_b64_tr_b16 v[132:133], v96 offset:576
	ds_read_b128 v[134:137], v24
	s_waitcnt lgkmcnt(3)
	v_mfma_f32_16x16x32_bf16 v[14:17], v[122:125], v[126:129], v[14:17]
	ds_read_b64_tr_b16 v[126:127], v97 offset:4608
	ds_read_b64_tr_b16 v[128:129], v97 offset:5184
	ds_read_b128 v[138:141], v24 offset:64
	ds_read_b64_tr_b16 v[142:143], v98
	ds_read_b64_tr_b16 v[144:145], v98 offset:576
	ds_read_b64_tr_b16 v[146:147], v99 offset:4608
	ds_read_b128 v[150:153], v25 offset:55296
	ds_read_b64_tr_b16 v[148:149], v99 offset:5184
	ds_read_b128 v[154:157], v25 offset:55360
	ds_read_b128 v[158:161], v100 offset:36864
	ds_read_b128 v[168:171], v78
	s_waitcnt lgkmcnt(11)
	v_mfma_f32_16x16x32_bf16 v[14:17], v[130:133], v[134:137], v[14:17]
	s_waitcnt lgkmcnt(0)
	v_pk_mul_f32 v[8:9], v[8:9], v[170:171]
	v_pk_mul_f32 v[6:7], v[6:7], v[168:169]
	v_mfma_f32_16x16x32_bf16 v[14:17], v[126:129], v[138:141], v[14:17]
	v_mul_f32_e64 v4, v4, v170
	v_mul_f32_e64 v5, v5, v171
	v_pk_mul_f32 v[2:3], v[2:3], v[168:169]
	v_mfma_f32_16x16x32_bf16 v[6:9], v[158:161], v[134:137], v[6:9]
	ds_read_b128 v[134:137], v100 offset:36928
	s_waitcnt lgkmcnt(0)
	v_mfma_f32_16x16x32_bf16 v[6:9], v[134:137], v[138:141], v[6:9]
	ds_read_b128 v[138:141], v100 offset:46080
	v_mfma_f32_16x16x32_bf16 v[14:17], v[142:145], v[150:153], v[14:17]
	s_waitcnt lgkmcnt(0)
	v_mfma_f32_16x16x32_bf16 v[6:9], v[138:141], v[150:153], v[6:9]
	ds_read_b128 v[150:153], v100 offset:46144
	v_mfma_f32_16x16x32_bf16 v[14:17], v[146:149], v[154:157], v[14:17]
	s_waitcnt lgkmcnt(0)
	v_mfma_f32_16x16x32_bf16 v[6:9], v[150:153], v[154:157], v[6:9]
	ds_read_b128 v[154:157], v23 offset:64512
	s_nop 4
	global_store_dword v[64:65], v14, off offset:-512
	global_store_dword v[64:65], v15, off offset:-256
	s_waitcnt lgkmcnt(0)
	v_mfma_f32_16x16x32_bf16 v[10:13], v[10:13], v[154:157], 0
	ds_read_b128 v[154:157], v23 offset:64576
	s_waitcnt lgkmcnt(0)
	v_mfma_f32_16x16x32_bf16 v[10:13], v[122:125], v[154:157], v[10:13]
	ds_read_b128 v[122:125], v21
	s_waitcnt lgkmcnt(0)
	v_mfma_f32_16x16x32_bf16 v[10:13], v[130:133], v[122:125], v[10:13]
	ds_read_b128 v[130:133], v21 offset:64
	v_mfma_f32_16x16x32_bf16 v[2:5], v[158:161], v[122:125], v[2:5]
	s_waitcnt lgkmcnt(0)
	v_mfma_f32_16x16x32_bf16 v[10:13], v[126:129], v[130:133], v[10:13]
	ds_read_b128 v[126:129], v23 offset:55296
	ds_read_b128 v[22:25], v23 offset:55360
	v_mfma_f32_16x16x32_bf16 v[2:5], v[134:137], v[130:133], v[2:5]
	s_waitcnt lgkmcnt(1)
	v_mfma_f32_16x16x32_bf16 v[10:13], v[142:145], v[126:129], v[10:13]
	v_mfma_f32_16x16x32_bf16 v[2:5], v[138:141], v[126:129], v[2:5]
	s_waitcnt lgkmcnt(0)
	v_mfma_f32_16x16x32_bf16 v[10:13], v[146:149], v[22:25], v[10:13]
	global_store_dword v[64:65], v16, off
	global_store_dword v[64:65], v17, off offset:256
	s_nop 5
	global_store_dword v[64:65], v10, off offset:-448
	global_store_dword v[64:65], v11, off offset:-192
	global_store_dword v[64:65], v12, off offset:64
	global_store_dword v[64:65], v13, off offset:320
	v_mfma_f32_16x16x32_bf16 v[2:5], v[150:153], v[22:25], v[2:5]
	s_cbranch_vccnz .LBB0_861
	s_waitcnt vmcnt(30)
	v_pk_mul_f32 v[46:47], v[42:43], v[40:41]
	v_mov_b32_e32 v57, v41
	s_waitcnt vmcnt(29)
	v_pk_mul_f32 v[48:49], v[44:45], v[46:47]
	v_mov_b32_e32 v56, v40
	s_waitcnt vmcnt(28)
	v_pk_mul_f32 v[50:51], v[54:55], v[48:49]
	ds_bpermute_b32 v52, v27, v50
	ds_bpermute_b32 v53, v27, v51
	s_and_saveexec_b64 s[10:11], s[36:37]
	s_cbranch_execz .LBB0_860
	s_add_i32 s12, s9, 0x200
	s_and_b32 s12, s12, 0x200
	v_lshl_add_u32 v10, s12, 2, v31
	s_waitcnt lgkmcnt(0)
	v_pk_mul_f32 v[56:57], v[40:41], v[52:53]
	v_pk_mul_f32 v[46:47], v[46:47], v[52:53]
	v_pk_mul_f32 v[48:49], v[48:49], v[52:53]
	v_pk_mul_f32 v[50:51], v[50:51], v[52:53]
	ds_write_b64 v10, v[50:51]
	s_branch .LBB0_860
